# P4: odd workgroups run the bandwidth-bound RWKV combine before the compute-bound SSD output units (even ones after), so the two overlap across CUs
# speedup vs baseline: 1.0026x; 1.0026x over previous
; #define LAS __attribute__((address_space(3)))
; #define INP(k) (*(const float* const volatile __attribute__((address_space(4)))*)(ka + 8 * (k)))
; __device__ __forceinline__ void ssd_s3_unit(LAS unsigned char* lds, int unit, const bf16_t* P0, const float* cw, const float* cb, const float* dt_bias, const float* a_log, const float* dskip, const float* norm_w,
;                                             const bf16_t* STATES, bf16_t* OMIX) {
;     const int tid = threadIdx.x, lane = tid & 63, w = tid >> 6, fr = lane & 15, fq = lane >> 4;
;     const int g = unit & 1, c = (unit >> 1) & 31, b = unit >> 6, t0 = c * 128;
;     LAS bf16_t* CS = (LAS bf16_t*)lds; LAS bf16_t* BS = (LAS bf16_t*)(lds + 34816); LAS bf16_t* XT = (LAS bf16_t*)(lds + 69632);
;     LAS float* dtS = (LAS float*)(lds + 139264); LAS float* cumS = (LAS float*)(lds + 143360); LAS float* totS = (LAS float*)(lds + 147456);
;     const bf16_t* Pb = P0 + (size_t)b * SEQ * ABPAD;
;     __syncthreads();
;     ssd_conv8<4, false>(BS, (tid & 15) * 8, 512 + g * 128 + (tid & 15) * 8, (tid >> 4) * 4, Pb, t0, cw, cb);
;     ssd_conv8<4, false>(CS, (tid & 15) * 8, 768 + g * 128 + (tid & 15) * 8, (tid >> 4) * 4, Pb, t0, cw, cb);
;     ssd_conv8<8, true>(XT, (tid & 31) * 8, g * 256 + (tid & 31) * 8, (tid >> 5) * 8, Pb, t0, cw, cb);
;     ssd_dt_cum(dtS, cumS, totS, Pb + (size_t)t0 * ABPAD, g, w, lane, dt_bias, a_log);
;     __syncthreads();
;     const int l = 16 * w + fr;
;     f32x4 sc[8];
; #pragma unroll
;     for (int nt = 0; nt < 8; ++nt) sc[nt] = (f32x4){0.f, 0.f, 0.f, 0.f};
; #pragma unroll
;     for (int ks = 0; ks < 4; ++ks) { const bf16x8 afr = ldsfrag(CS, SLD, 16 * w, ks * 32, fr, fq);
; #pragma unroll
;         for (int nt = 0; nt < 8; ++nt) sc[nt] = mfma16(ldsfrag(BS, SLD, nt * 16, ks * 32, fr, fq), afr, sc[nt]); }
;     __syncthreads();
;     LAS bf16_t* Mw = BS + w * 16 * SLD;
;     const size_t row = (size_t)b * SEQ + t0 + l; float ss = 0.f;
; #pragma unroll 1
;     for (int j = 0; j < 4; ++j) {
; __global__ void __launch_bounds__(512, 2) mk_fwd(Args args) {
;     ...
;         for (int r2 = 0; r2 <= DUP_S3; ++r2)
;         for (int u = bx; u < 1024; u += G) ssd_s3_unit(lds, u, P, INP(16), INP(17), INP(18), INP(19), INP(20), INP(21), OMIX1, OMIX0);
;         __syncthreads();
;         { LOCAL_IDS rwkv_combine(P, H, BONUS, GG, INP(5), INP(14), INP(15), OMIX0, gw, NGW, lane); }
.LBB0_789:
	v_readlane_b32 s2, v253, 8
	s_cmp_lt_i32 s2, 5
	v_readlane_b32 s4, v253, 0
	s_cselect_b64 s[2:3], -1, 0
	v_readlane_b32 s5, v253, 1
	s_add_u32 s4, s4, 0x2c000000
	s_addc_u32 s5, s5, 0
	v_writelane_b32 v253, s4, 58
	s_and_b64 s[0:1], s[2:3], s[0:1]
	s_nop 0
	v_writelane_b32 v253, s5, 59
	v_writelane_b32 v253, s0, 60
	s_andn2_b64 vcc, exec, s[0:1]
	s_nop 0
	v_writelane_b32 v253, s1, 61
	v_writelane_b32 v253, s58, 62
	s_nop 1
	v_writelane_b32 v253, s59, 63
	s_cbranch_vccnz .Lp4_end
	s_bitcmp1_b32 s90, 0
	s_cbranch_scc0 .Lp4_s3
	s_mov_b64 s[58:59], s[64:65]
	s_branch .Lp4_comb
.Lp4_s3:
	s_cmpk_lt_i32 s90, 0x400
	s_mov_b64 s[58:59], s[64:65]
	s_cbranch_scc0 .LBB0_975
	v_lshrrev_b32_e32 v4, 2, v200
	v_and_b32_e32 v146, 0xf8, v4
	s_add_i32 s0, 0, 0x11000
	v_and_b32_e32 v0, 63, v200
	v_and_b32_e32 v144, 0xfc, v4
	v_lshl_add_u32 v10, v146, 1, s0
	s_movk_i32 s0, 0x1c00
	v_mov_b32_e32 v4, 0xd00
	v_mad_u32_u24 v149, v0, s0, v4
	v_mov_b32_e32 v4, 0x1b00
	v_mad_u32_u24 v150, v0, s0, v4
	v_cmp_eq_u32_e64 s[0:1], 0, v0
	v_lshlrev_b32_e32 v2, 3, v200
	v_and_b32_e32 v117, 0x78, v2
	v_writelane_b32 v254, s0, 0
	v_and_b32_e32 v145, 0xf8, v2
	v_bfe_u32 v2, v200, 6, 1
	v_writelane_b32 v254, s1, 1
	v_cmp_gt_u32_e64 s[0:1], 2, v0
	v_lshrrev_b32_e32 v1, 6, v200
	v_lshlrev_b32_e32 v148, 3, v2
	v_writelane_b32 v254, s0, 2
	v_mov_b32_e32 v109, 0
	v_and_b32_e32 v3, 15, v200
	v_writelane_b32 v254, s1, 3
	v_cmp_gt_u32_e64 s[0:1], 4, v0
	v_bfe_u32 v5, v200, 4, 2
	v_and_b32_e32 v106, 48, v200
	v_writelane_b32 v254, s0, 4
	v_mov_b32_e32 v107, v109
	v_lshl_or_b32 v104, v1, 4, v3
	v_writelane_b32 v254, s1, 5
	v_cmp_gt_u32_e64 s[0:1], 8, v0
	v_mul_u32_u24_e32 v4, 0x1100, v1
	s_movk_i32 s33, 0x110
	v_writelane_b32 v254, s0, 6
	v_mul_u32_u24_e32 v14, 0x110, v3
	v_lshl_add_u32 v7, v117, 1, 0
	v_writelane_b32 v254, s1, 7
	v_cmp_gt_u32_e64 s[0:1], 16, v0
	v_mul_u32_u24_e32 v9, 0x110, v144
	v_mul_u32_u24_e32 v11, 0x110, v145
	v_writelane_b32 v254, s0, 8
	v_mad_u32_u24 v12, v104, s33, 0
	v_add_u32_e32 v13, 0, v106
	v_writelane_b32 v254, s1, 9
	v_cmp_gt_u32_e64 s[0:1], 32, v0
	v_add3_u32 v154, 0, v4, v14
	v_lshrrev_b32_e32 v147, 7, v200
	v_writelane_b32 v254, s0, 10
	v_mov_b32_e32 v113, v109
	v_mov_b32_e32 v105, v109
	v_writelane_b32 v254, s1, 11
	v_cmp_eq_u32_e64 s[0:1], 0, v2
	v_lshlrev_b32_e32 v2, 9, v1
	v_lshl_or_b32 v0, v0, 3, v2
	v_writelane_b32 v254, s0, 12
	v_lshlrev_b32_e32 v2, 3, v5
	v_or_b32_e32 v112, 0x2c000440, v2
	v_writelane_b32 v254, s1, 13
	s_add_i32 s0, 0, 0x22000
	v_add_u32_e32 v151, s0, v0
	s_add_i32 s0, 0, 0x23000
	v_add_u32_e32 v152, s0, v0
	s_add_i32 s0, 0, 0x24000
	v_lshl_add_u32 v153, v1, 2, s0
	v_readlane_b32 s0, v253, 62
	v_readlane_b32 s1, v253, 63
	v_lshlrev_b32_e32 v1, 5, v1
	v_lshlrev_b32_e32 v0, 7, v3
	v_lshl_add_u64 v[110:111], s[0:1], 0, v[106:107]
	v_lshlrev_b32_e32 v107, 2, v5
	v_cmp_le_u32_e64 s[0:1], v107, v104
	v_or_b32_e32 v15, 1, v107
	v_or_b32_e32 v4, 0x800, v0
	v_writelane_b32 v253, s0, 48
	v_or_b32_e32 v6, 0x1000, v0
	v_or_b32_e32 v8, 0x1800, v0
	v_writelane_b32 v253, s1, 49
	v_cmp_lt_u32_e64 s[0:1], v107, v104
	v_mad_u32_u24 v166, v3, s33, v106
	v_or_b32_e32 v114, 0x10000e40, v2
	v_writelane_b32 v253, s0, 52
	v_mov_b32_e32 v115, v109
	v_lshl_or_b32 v116, v3, 8, v106
	v_writelane_b32 v253, s1, 53
	v_cmp_ge_u32_e64 s[0:1], v107, v104
	v_add_u32_e32 v167, v10, v11
	v_mov_b32_e32 v168, 0x3ecc95a3
	v_writelane_b32 v253, s0, 54
	v_add_u32_e32 v169, v13, v14
	v_add_u32_e32 v170, v154, v2
	v_writelane_b32 v253, s1, 55
	v_cmp_ge_u32_e64 s[0:1], v15, v104
	v_or_b32_e32 v15, 2, v107
	v_lshlrev_b32_e32 v108, 1, v0
	v_writelane_b32 v253, s0, 42
	v_lshlrev_b32_e32 v118, 1, v4
	v_lshlrev_b32_e32 v120, 1, v6
	v_writelane_b32 v253, s1, 43
	v_cmp_le_u32_e64 s[0:1], v15, v104
	v_lshlrev_b32_e32 v122, 1, v8
	v_mov_b32_e32 v171, 0x358637bd
	v_writelane_b32 v253, s0, 46
	v_mov_b32_e32 v172, 0x800
	v_add_u32_e32 v173, v7, v9
	v_writelane_b32 v253, s1, 47
	v_cmp_ge_u32_e64 s[0:1], v15, v104
	v_or_b32_e32 v15, 3, v107
	v_mov_b32_e32 v174, 0xc00
	v_writelane_b32 v253, s0, 50
	v_mov_b32_e32 v124, 0x3f317218
	v_mov_b32_e32 v175, 0x7f800000
	v_writelane_b32 v253, s1, 51
	v_cmp_le_u32_e64 s[0:1], v15, v104
	v_mov_b32_e32 v176, 0x7fc00000
	v_mov_b32_e32 v177, 0xff800000
	v_writelane_b32 v253, s0, 44
	v_add_u32_e32 v178, v12, v106
	s_nop 0
	v_writelane_b32 v253, s1, 45
	v_cmp_ge_u32_e64 s[0:1], v15, v104
	v_or_b32_e32 v15, 16, v107
	s_nop 0
	v_writelane_b32 v253, s0, 40
	s_nop 1
	v_writelane_b32 v253, s1, 41
	v_cmp_le_u32_e64 s[0:1], v15, v104
	s_nop 1
	v_writelane_b32 v253, s0, 38
	s_nop 1
	v_writelane_b32 v253, s1, 39
	v_cmp_ge_u32_e64 s[0:1], v15, v104
	v_or_b32_e32 v15, 17, v107
	v_readlane_b32 s54, v253, 34
	v_writelane_b32 v254, s0, 14
	v_readlane_b32 s55, v253, 35
	s_bitcmp1_b32 s54, 0
	v_writelane_b32 v254, s1, 15
	v_cmp_le_u32_e64 s[0:1], v15, v104
	s_mov_b32 s56, s54
	s_cselect_b64 s[54:55], -1, 0
	v_writelane_b32 v254, s0, 16
	s_mov_b32 s33, s56
	s_nop 0
	v_writelane_b32 v254, s1, 17
	v_cmp_ge_u32_e64 s[0:1], v15, v104
	v_or_b32_e32 v15, 18, v107
	s_nop 0
	v_writelane_b32 v254, s0, 18
	s_nop 1
	v_writelane_b32 v254, s1, 19
	v_cmp_le_u32_e64 s[0:1], v15, v104
	s_nop 1
	v_writelane_b32 v254, s0, 20
	s_nop 1
	v_writelane_b32 v254, s1, 21
; #define LAS __attribute__((address_space(3)))
; __device__ __forceinline__ float softplusf_(float x) { return x > 20.f ? x : log1pf(__expf(x)); }
; __device__ __forceinline__ void ssd_dt_cum(LAS float* dtS, LAS float* cumS, LAS float* totS, const bf16_t* Prow0, int g, int w, int lane, const float* dt_bias, const float* a_log) {
;     const int j = w >> 1, d = w & 1, head = g * 4 + j;
;     const float bias = dt_bias[d * 8 + head], A = -__expf(a_log[d * 8 + head]);
;     const float x0 = bf2f(Prow0[(size_t)(2 * lane) * ABPAD + 3328 + head]), x1 = bf2f(Prow0[(size_t)(2 * lane + 1) * ABPAD + 3328 + head]);
;     const float dt0 = softplusf_(x0 + bias), dt1 = softplusf_(x1 + bias), la0 = dt0 * A, la1 = dt1 * A;
;     const float s = la0 + la1; float inc = s;
; #pragma unroll
;     for (int off = 1; off < 64; off <<= 1) { const float n = __shfl_up(inc, off); if (lane >= off) inc += n; }
;     const float tot = __shfl(inc, 63), exc = inc - s;
;     float c0, c1; if (d == 0) { c0 = exc + la0; c1 = inc; } else { c0 = tot - exc; c1 = tot - exc - la0; }
;     dtS[w * 128 + 2 * lane] = dt0; dtS[w * 128 + 2 * lane + 1] = dt1; cumS[w * 128 + 2 * lane] = c0; cumS[w * 128 + 2 * lane + 1] = c1;
;     if (lane == 0) totS[w] = tot;
; __device__ __forceinline__ void ssd_s3_unit(LAS unsigned char* lds, int unit, const bf16_t* P0, const float* cw, const float* cb, const float* dt_bias, const float* a_log, const float* dskip, const float* norm_w,
;                                             const bf16_t* STATES, bf16_t* OMIX) {
;     ...
;         for (int nt = 0; nt < 8; ++nt) { float mv[4];
; #pragma unroll
;             for (int i = 0; i < 4; ++i) { const int s = nt * 16 + fq * 4 + i;
;                 const float ff = (s <= l) ? __expf(cfl - cf[s]) * df[s] : 0.f; const float fb = (s >= l) ? __expf(cbl - cbw[s]) * db[s] : 0.f;
;                 mv[i] = sc[nt][i] * (ff + fb); }
	v_cmp_ge_u32_e64 s[0:1], v15, v104
	v_or_b32_e32 v15, 19, v107
	s_nop 0
	v_writelane_b32 v254, s0, 22
	s_nop 1
	v_writelane_b32 v254, s1, 23
	v_cmp_le_u32_e64 s[0:1], v15, v104
	s_nop 1
	v_writelane_b32 v254, s0, 24
	s_nop 1
	v_writelane_b32 v254, s1, 25
	v_cmp_ge_u32_e64 s[0:1], v15, v104
	v_or_b32_e32 v15, 32, v107
	s_nop 0
	v_writelane_b32 v254, s0, 26
	s_nop 1
	v_writelane_b32 v254, s1, 27
	v_cmp_le_u32_e64 s[0:1], v15, v104
	s_nop 1
	v_writelane_b32 v254, s0, 28
	s_nop 1
	v_writelane_b32 v254, s1, 29
	v_cmp_ge_u32_e64 s[0:1], v15, v104
	v_or_b32_e32 v15, 33, v107
	s_nop 0
	v_writelane_b32 v254, s0, 30
	s_nop 1
	v_writelane_b32 v254, s1, 31
	v_cmp_le_u32_e64 s[0:1], v15, v104
	s_nop 1
	v_writelane_b32 v254, s0, 32
	s_nop 1
	v_writelane_b32 v254, s1, 33
	v_cmp_ge_u32_e64 s[0:1], v15, v104
	v_or_b32_e32 v15, 34, v107
	s_nop 0
	v_writelane_b32 v254, s0, 34
	s_nop 1
	v_writelane_b32 v254, s1, 35
	v_cmp_le_u32_e64 s[0:1], v15, v104
	s_nop 1
	v_writelane_b32 v254, s0, 36
	s_nop 1
	v_writelane_b32 v254, s1, 37
	v_cmp_ge_u32_e64 s[0:1], v15, v104
	v_or_b32_e32 v15, 35, v107
	v_cmp_le_u32_e64 s[66:67], v15, v104
	v_cmp_ge_u32_e64 s[68:69], v15, v104
	v_or_b32_e32 v15, 48, v107
	v_cmp_le_u32_e64 s[70:71], v15, v104
	v_cmp_ge_u32_e64 s[72:73], v15, v104
	v_or_b32_e32 v15, 49, v107
	v_cmp_le_u32_e64 s[74:75], v15, v104
	v_cmp_ge_u32_e64 s[76:77], v15, v104
	v_or_b32_e32 v15, 50, v107
	v_cmp_le_u32_e64 s[78:79], v15, v104
	v_cmp_ge_u32_e64 s[80:81], v15, v104
	v_or_b32_e32 v15, 51, v107
	v_cmp_le_u32_e64 s[82:83], v15, v104
	v_cmp_ge_u32_e64 s[84:85], v15, v104
	v_or_b32_e32 v15, 64, v107
	v_cmp_le_u32_e64 s[86:87], v15, v104
	v_cmp_ge_u32_e64 s[88:89], v15, v104
	v_or_b32_e32 v15, 0x41, v107
	v_cmp_le_u32_e64 s[90:91], v15, v104
	v_cmp_ge_u32_e64 s[92:93], v15, v104
	v_or_b32_e32 v15, 0x42, v107
	v_cmp_le_u32_e64 s[94:95], v15, v104
	v_cmp_ge_u32_e64 s[96:97], v15, v104
	v_or_b32_e32 v15, 0x43, v107
	v_cmp_le_u32_e64 s[4:5], v15, v104
	v_cmp_ge_u32_e64 s[8:9], v15, v104
	v_or_b32_e32 v15, 0x50, v107
	v_cmp_le_u32_e64 s[10:11], v15, v104
	v_cmp_ge_u32_e64 s[12:13], v15, v104
	v_or_b32_e32 v15, 0x51, v107
	v_cmp_le_u32_e64 s[14:15], v15, v104
	v_cmp_ge_u32_e64 s[16:17], v15, v104
	v_or_b32_e32 v15, 0x52, v107
	v_cmp_le_u32_e64 s[6:7], v15, v104
	v_cmp_ge_u32_e64 s[18:19], v15, v104
	v_or_b32_e32 v15, 0x53, v107
	v_writelane_b32 v254, s0, 38
	v_cmp_le_u32_e64 s[20:21], v15, v104
	v_cmp_ge_u32_e64 s[2:3], v15, v104
	v_or_b32_e32 v15, 0x60, v107
	v_writelane_b32 v254, s1, 39
	v_cmp_le_u32_e64 s[0:1], v15, v104
	v_cmp_ge_u32_e64 s[22:23], v15, v104
	v_or_b32_e32 v15, 0x61, v107
	v_cmp_le_u32_e64 s[24:25], v15, v104
	v_cmp_ge_u32_e64 s[26:27], v15, v104
	v_or_b32_e32 v15, 0x62, v107
	v_cmp_le_u32_e64 s[28:29], v15, v104
	v_cmp_ge_u32_e64 s[30:31], v15, v104
	v_or_b32_e32 v15, 0x63, v107
	v_cmp_le_u32_e64 s[34:35], v15, v104
	v_cmp_ge_u32_e64 s[36:37], v15, v104
	v_or_b32_e32 v15, 0x70, v107
	v_cmp_le_u32_e64 s[38:39], v15, v104
	v_cmp_ge_u32_e64 s[40:41], v15, v104
	v_or_b32_e32 v15, 0x71, v107
	v_cmp_le_u32_e64 s[42:43], v15, v104
	v_cmp_ge_u32_e64 s[44:45], v15, v104
	v_or_b32_e32 v15, 0x72, v107
	v_cmp_le_u32_e64 s[46:47], v15, v104
	v_cmp_ge_u32_e64 s[48:49], v15, v104
	v_or_b32_e32 v15, 0x73, v107
	v_cmp_le_u32_e64 s[50:51], v15, v104
	v_cmp_ge_u32_e64 s[52:53], v15, v104
	v_mbcnt_lo_u32_b32 v15, -1, 0
	v_mbcnt_hi_u32_b32 v15, -1, v15
	v_and_b32_e32 v16, 64, v15
	v_add_u32_e32 v17, -1, v15
	v_cmp_lt_i32_e32 vcc, v17, v16
	v_writelane_b32 v254, s54, 40
	s_nop 0
	v_cndmask_b32_e32 v17, v17, v15, vcc
	v_lshlrev_b32_e32 v155, 2, v17
	v_add_u32_e32 v17, -2, v15
	v_cmp_lt_i32_e32 vcc, v17, v16
	v_writelane_b32 v254, s55, 41
	s_load_dwordx2 s[54:55], s[58:59], 0x130
	v_cndmask_b32_e32 v17, v17, v15, vcc
	v_lshlrev_b32_e32 v156, 2, v17
	v_add_u32_e32 v17, -4, v15
	v_cmp_lt_i32_e32 vcc, v17, v16
	s_waitcnt lgkmcnt(0)
	s_bitcmp1_b32 s54, 0
	s_cselect_b64 s[54:55], -1, 0
	v_cndmask_b32_e32 v17, v17, v15, vcc
	v_lshlrev_b32_e32 v157, 2, v17
	v_add_u32_e32 v17, -8, v15
	v_cmp_lt_i32_e32 vcc, v17, v16
	v_writelane_b32 v254, s54, 42
	s_nop 0
	v_cndmask_b32_e32 v17, v17, v15, vcc
	v_lshlrev_b32_e32 v158, 2, v17
	v_add_u32_e32 v17, -16, v15
	v_cmp_lt_i32_e32 vcc, v17, v16
	v_writelane_b32 v254, s55, 43
	s_movk_i32 s54, 0x3c0
	v_cndmask_b32_e32 v17, v17, v15, vcc
	v_lshlrev_b32_e32 v159, 2, v17
	v_subrev_u32_e32 v17, 32, v15
	v_cmp_lt_i32_e32 vcc, v17, v16
	v_add_u32_e32 v16, 64, v16
	s_nop 0
	v_cndmask_b32_e32 v17, v17, v15, vcc
	v_lshlrev_b32_e32 v160, 2, v17
	v_bfrev_b32_e32 v17, 0.5
	v_lshl_or_b32 v161, v15, 2, v17
	v_xor_b32_e32 v17, 16, v15
	v_cmp_lt_i32_e32 vcc, v17, v16
	s_nop 1
	v_cndmask_b32_e32 v17, v15, v17, vcc
	v_lshlrev_b32_e32 v162, 2, v17
	v_xor_b32_e32 v17, 32, v15
	v_cmp_lt_i32_e32 vcc, v17, v16
	s_nop 1
	v_cndmask_b32_e32 v15, v15, v17, vcc
	v_lshlrev_b32_e32 v163, 2, v15
	v_lshlrev_b32_e32 v15, 2, v3
	v_and_or_b32 v164, v200, s54, v15
	s_movk_i32 s54, 0x440
	v_mad_u32_u24 v1, v5, s54, v1
	v_readlane_b32 s54, v253, 0
	v_readlane_b32 s55, v253, 1
	s_add_u32 s54, s54, 0x2c000440
	s_addc_u32 s55, s55, 0
	v_writelane_b32 v254, s54, 44
	v_lshl_or_b32 v165, v3, 1, v1
	s_nop 0
	v_writelane_b32 v254, s55, 45
	s_mov_b64 s[54:55], 0x80

; #define INP(k) (*(const float* const volatile __attribute__((address_space(4)))*)(ka + 8 * (k)))
; __global__ void __launch_bounds__(512, 2) mk_fwd(Args args) {
;     ...
;         for (int r2 = 0; r2 <= DUP_S3; ++r2)
;         for (int u = bx; u < 1024; u += G) ssd_s3_unit(lds, u, P, INP(16), INP(17), INP(18), INP(19), INP(20), INP(21), OMIX1, OMIX0);
;         __syncthreads();
;         { LOCAL_IDS rwkv_combine(P, H, BONUS, GG, INP(5), INP(14), INP(15), OMIX0, gw, NGW, lane); }
.LBB0_975:
	v_readlane_b32 s0, v253, 34
	s_bitcmp1_b32 s0, 0
	s_cbranch_scc1 .Lp4_odd_after_s3

; #define INP(k) (*(const float* const volatile __attribute__((address_space(4)))*)(ka + 8 * (k)))
; __global__ void __launch_bounds__(512, 2) mk_fwd(Args args) {
;     ...
;         for (int r2 = 0; r2 <= DUP_S3; ++r2)
;         for (int u = bx; u < 1024; u += G) ssd_s3_unit(lds, u, P, INP(16), INP(17), INP(18), INP(19), INP(20), INP(21), OMIX1, OMIX0);
;         __syncthreads();
;         { LOCAL_IDS rwkv_combine(P, H, BONUS, GG, INP(5), INP(14), INP(15), OMIX0, gw, NGW, lane); }
;     }
.Lp4_odd_after_s3:
	v_readlane_b32 s58, v253, 24
	v_readlane_b32 s59, v253, 25
	s_load_dwordx2 s[96:97], s[58:59], 0x130
	v_readlane_b32 s90, v253, 34
	v_readlane_b32 s72, v253, 36
	v_readlane_b32 s60, v253, 26
	v_readlane_b32 s94, v253, 32
	v_readlane_b32 s73, v253, 37
	v_readlane_b32 s61, v253, 27
	v_readlane_b32 s91, v253, 35
	v_readlane_b32 s95, v253, 33
	s_waitcnt vmcnt(0) lgkmcnt(0)
	s_barrier
	s_branch .Lp4_end
